# grid barrier: the middle arriver of each XCD issues an early L2 write-back so the last arriver's flush is shorter
# speedup vs baseline: 1.0026x; 1.0026x over previous
; template <int N> DI void wait_vm() { asm volatile("s_waitcnt vmcnt(%0)" ::"n"(N) : "memory"); }
; DI void fast_grid_barrier(unsigned* ctr, unsigned target) {
;     wait_vm<0>();
;     __syncthreads();
;     if (threadIdx.x == 0) {
;         __builtin_amdgcn_fence(__ATOMIC_RELEASE, "agent");
;         __hip_atomic_fetch_add(ctr, 1u, __ATOMIC_RELAXED, __HIP_MEMORY_SCOPE_AGENT);
;         while (__hip_atomic_load(ctr, __ATOMIC_RELAXED, __HIP_MEMORY_SCOPE_AGENT) < target) __builtin_amdgcn_s_sleep(6);
;         __builtin_amdgcn_fence(__ATOMIC_ACQUIRE, "agent");
;     }
;     __syncthreads();
; }
.Lxb_follow:
	s_lshr_b32 s3, s3, 1
	s_sub_u32 s7, s7, s3
	s_cmp_eq_u32 s6, s7
	s_cbranch_scc0 .Lxb_poll
	buffer_wbl2 sc1
